# all 6 GEMM K-loops (st0,4,5,6,7,8): ds_reads issued right after barrier, LDS-DMA issues interleaved one per MFMA in first sub-step
# speedup vs baseline: 1.0308x; 1.0289x over previous
.LBB0_34:
	s_add_i32 s1, s0, 0x10000
	s_and_b32 s13, s1, 0x10000
	s_and_b32 s0, s0, 0x10000
	s_add_i32 s0, s0, 16
	v_add_u32_e32 v190, s13, v210
	s_nop 0
	v_readfirstlane_b32 s13, v190
	s_waitcnt vmcnt(0)
	s_barrier
	v_add_u32_e32 v166, s0, v182
	v_add_u32_e32 v167, s0, v204
	v_add_u32_e32 v162, v166, v227
	v_add_u32_e32 v168, v167, v227
	ds_read_b128 v[150:153], v162
	ds_read_b128 v[154:157], v162 offset:4096
	ds_read_b128 v[158:161], v162 offset:8192
	ds_read_b128 v[162:165], v162 offset:12288
	ds_read_b128 v[170:173], v168 offset:32768
	ds_read_b128 v[174:177], v168 offset:36864
	v_lshl_add_u64 v[178:179], v[142:143], 0, s[2:3]
	s_mov_b32 m0, s13
	s_nop 0
	global_load_lds_dwordx4 v[178:179], off
	v_lshl_add_u64 v[178:179], v[140:141], 0, s[2:3]
	s_add_i32 s14, s13, 0x2000
	s_mov_b32 m0, s14
	s_nop 0
	global_load_lds_dwordx4 v[178:179], off
	s_waitcnt lgkmcnt(1)
	v_mfma_f32_32x32x16_bf16 v[112:127], v[170:173], v[150:153], v[112:127]
	v_lshl_add_u64 v[178:179], v[138:139], 0, s[2:3]
	s_add_i32 s14, s13, 0x4000
	s_mov_b32 m0, s14
	s_nop 0
	global_load_lds_dwordx4 v[178:179], off
	v_add_u32_e32 v168, v167, v228
	v_mfma_f32_32x32x16_bf16 v[96:111], v[170:173], v[154:157], v[96:111]
	v_lshl_add_u64 v[178:179], v[136:137], 0, s[2:3]
	s_add_i32 s14, s13, 0x6000
	s_mov_b32 m0, s14
	s_nop 0
	global_load_lds_dwordx4 v[178:179], off
	v_mfma_f32_32x32x16_bf16 v[80:95], v[170:173], v[158:161], v[80:95]
	v_lshl_add_u64 v[178:179], v[134:135], 0, s[2:3]
	s_add_i32 s14, s13, 0x8000
	s_mov_b32 m0, s14
	s_nop 0
	global_load_lds_dwordx4 v[178:179], off
	v_mfma_f32_32x32x16_bf16 v[64:79], v[170:173], v[162:165], v[64:79]
	v_lshl_add_u64 v[178:179], v[132:133], 0, s[2:3]
	s_add_i32 s14, s13, 0xa000
	s_mov_b32 m0, s14
	s_nop 0
	global_load_lds_dwordx4 v[178:179], off
	s_waitcnt lgkmcnt(0)
	v_mfma_f32_32x32x16_bf16 v[48:63], v[174:177], v[150:153], v[48:63]
	v_lshl_add_u64 v[178:179], v[130:131], 0, s[2:3]
	s_add_i32 s14, s13, 0xc000
	s_mov_b32 m0, s14
	s_nop 0
	global_load_lds_dwordx4 v[178:179], off
	v_mfma_f32_32x32x16_bf16 v[32:47], v[174:177], v[154:157], v[32:47]
	v_lshl_add_u64 v[178:179], v[128:129], 0, s[2:3]
	s_add_i32 s14, s13, 0xe000
	s_mov_b32 m0, s14
	s_nop 0
	global_load_lds_dwordx4 v[178:179], off
	s_add_u32 s2, s2, 0x80
	s_addc_u32 s3, s3, 0
	s_cmpk_lg_i32 s2, 0x1f80
	v_mfma_f32_32x32x16_bf16 v[16:31], v[174:177], v[158:161], v[16:31]
	v_mfma_f32_32x32x16_bf16 v[0:15], v[174:177], v[162:165], v[0:15]
	v_add_u32_e32 v162, v166, v228
	ds_read_b128 v[150:153], v162
	ds_read_b128 v[154:157], v162 offset:4096
	ds_read_b128 v[158:161], v162 offset:8192
	ds_read_b128 v[162:165], v162 offset:12288
	ds_read_b128 v[170:173], v168 offset:32768
	ds_read_b128 v[174:177], v168 offset:36864
	v_add_u32_e32 v168, v167, v229
	s_waitcnt lgkmcnt(1)
	v_mfma_f32_32x32x16_bf16 v[112:127], v[170:173], v[150:153], v[112:127]
	v_mfma_f32_32x32x16_bf16 v[96:111], v[170:173], v[154:157], v[96:111]
	v_mfma_f32_32x32x16_bf16 v[80:95], v[170:173], v[158:161], v[80:95]
	v_mfma_f32_32x32x16_bf16 v[64:79], v[170:173], v[162:165], v[64:79]
	s_waitcnt lgkmcnt(0)
	v_mfma_f32_32x32x16_bf16 v[48:63], v[174:177], v[150:153], v[48:63]
	v_mfma_f32_32x32x16_bf16 v[32:47], v[174:177], v[154:157], v[32:47]
	v_mfma_f32_32x32x16_bf16 v[16:31], v[174:177], v[158:161], v[16:31]
	v_mfma_f32_32x32x16_bf16 v[0:15], v[174:177], v[162:165], v[0:15]
	v_add_u32_e32 v162, v166, v229
	ds_read_b128 v[150:153], v162
	ds_read_b128 v[154:157], v162 offset:4096
	ds_read_b128 v[158:161], v162 offset:8192
	ds_read_b128 v[162:165], v162 offset:12288
	ds_read_b128 v[170:173], v168 offset:32768
	ds_read_b128 v[174:177], v168 offset:36864
	s_waitcnt lgkmcnt(1)
	v_mfma_f32_32x32x16_bf16 v[112:127], v[170:173], v[150:153], v[112:127]
	v_mfma_f32_32x32x16_bf16 v[96:111], v[170:173], v[154:157], v[96:111]
	v_mfma_f32_32x32x16_bf16 v[80:95], v[170:173], v[158:161], v[80:95]
	v_mfma_f32_32x32x16_bf16 v[64:79], v[170:173], v[162:165], v[64:79]
	s_waitcnt lgkmcnt(0)
	v_mfma_f32_32x32x16_bf16 v[48:63], v[174:177], v[150:153], v[48:63]
	v_mfma_f32_32x32x16_bf16 v[32:47], v[174:177], v[154:157], v[32:47]
	v_mfma_f32_32x32x16_bf16 v[16:31], v[174:177], v[158:161], v[16:31]
	v_mfma_f32_32x32x16_bf16 v[0:15], v[174:177], v[162:165], v[0:15]
	v_add_u32_e32 v162, v166, v230
	v_add_u32_e32 v166, v167, v230
	ds_read_b128 v[150:153], v162
	ds_read_b128 v[154:157], v162 offset:4096
	ds_read_b128 v[158:161], v162 offset:8192
	ds_read_b128 v[162:165], v162 offset:12288
	ds_read_b128 v[170:173], v166 offset:32768
	ds_read_b128 v[174:177], v166 offset:36864
	s_waitcnt lgkmcnt(1)
	v_mfma_f32_32x32x16_bf16 v[112:127], v[170:173], v[150:153], v[112:127]
	v_mfma_f32_32x32x16_bf16 v[96:111], v[170:173], v[154:157], v[96:111]
	v_mfma_f32_32x32x16_bf16 v[80:95], v[170:173], v[158:161], v[80:95]
	v_mfma_f32_32x32x16_bf16 v[64:79], v[170:173], v[162:165], v[64:79]
	s_waitcnt lgkmcnt(0)
	v_mfma_f32_32x32x16_bf16 v[48:63], v[174:177], v[150:153], v[48:63]
	v_mfma_f32_32x32x16_bf16 v[32:47], v[174:177], v[154:157], v[32:47]
	v_mfma_f32_32x32x16_bf16 v[16:31], v[174:177], v[158:161], v[16:31]
	v_mfma_f32_32x32x16_bf16 v[0:15], v[174:177], v[162:165], v[0:15]
	s_mov_b32 s0, s1
	s_cbranch_scc1 .LBB0_34
	s_add_i32 s23, s23, s78
	s_cmpk_gt_i32 s23, 0xff
	s_waitcnt vmcnt(0)
	s_barrier
	s_cselect_b64 s[2:3], -1, 0
	s_and_b64 vcc, exec, s[2:3]
	s_cbranch_vccnz .LBB0_37
	s_lshl_b32 s0, s23, 3
	s_lshr_b32 s1, s23, 5
	s_and_b32 s0, s0, 56
	s_add_i32 s0, s0, s1
	s_lshl_b32 s10, s23, 5
	v_lshl_add_u32 v130, s0, 8, v207
	s_and_b32 s10, s10, 0x300
	v_ashrrev_i32_e32 v131, 31, v130
	v_lshlrev_b64 v[132:133], 13, v[130:131]
	s_cmp_lg_u32 16, -1
	v_lshl_add_u64 v[132:133], v[146:147], 0, v[132:133]
	v_readfirstlane_b32 s0, v209
	s_cselect_b32 s1, 16, 0
	s_add_i32 s0, s0, s1
	s_mov_b32 s1, m0
	s_mov_b32 m0, s0
	s_nop 0
	global_load_lds_dwordx4 v[132:133], off
	s_mov_b32 m0, s1
	v_add_u32_e32 v132, 64, v130
	v_ashrrev_i32_e32 v133, 31, v132
	v_lshlrev_b64 v[132:133], 13, v[132:133]
	v_lshl_add_u64 v[132:133], v[146:147], 0, v[132:133]
	v_add_u32_e32 v128, s10, v208
	s_add_i32 s1, s0, 0x2000
	s_mov_b32 s10, m0
	s_mov_b32 m0, s1
	s_nop 0
	global_load_lds_dwordx4 v[132:133], off
	s_mov_b32 m0, s10
	v_add_u32_e32 v132, 0x80, v130
	v_ashrrev_i32_e32 v133, 31, v132
	v_add_u32_e32 v130, 0xc0, v130
	v_lshlrev_b64 v[132:133], 13, v[132:133]
	v_ashrrev_i32_e32 v131, 31, v130
	v_lshl_add_u64 v[132:133], v[146:147], 0, v[132:133]
	s_add_i32 s1, s0, 0x4000
	s_mov_b32 s10, m0
	s_mov_b32 m0, s1
	s_nop 0
	global_load_lds_dwordx4 v[132:133], off
	s_mov_b32 m0, s10
	v_lshlrev_b64 v[130:131], 13, v[130:131]
	v_ashrrev_i32_e32 v129, 31, v128
	v_lshl_add_u64 v[130:131], v[146:147], 0, v[130:131]
	s_add_i32 s1, s0, 0x6000
	s_mov_b32 s10, m0
	s_mov_b32 m0, s1
	s_nop 0
	global_load_lds_dwordx4 v[130:131], off
	s_mov_b32 m0, s10
	v_lshlrev_b64 v[128:129], 13, v[128:129]
	v_lshl_add_u64 v[128:129], v[144:145], 0, v[128:129]
	s_mov_b64 s[10:11], 0x200000
	v_lshl_add_u64 v[130:131], v[128:129], 0, s[10:11]
	s_add_i32 s1, s0, 0x8000
	s_mov_b32 s10, m0
	s_mov_b32 m0, s1
	s_nop 0
	global_load_lds_dwordx4 v[130:131], off
	s_mov_b32 m0, s10
	s_mov_b64 s[10:11], 0x280000
	v_lshl_add_u64 v[130:131], v[128:129], 0, s[10:11]
	s_add_i32 s1, s0, 0xa000
	s_mov_b32 s10, m0
	s_mov_b32 m0, s1
	s_nop 0
	global_load_lds_dwordx4 v[130:131], off
	s_mov_b32 m0, s10
	s_mov_b64 s[10:11], 0x300000
	v_lshl_add_u64 v[130:131], v[128:129], 0, s[10:11]
	s_add_i32 s1, s0, 0xc000
	s_mov_b32 s10, m0
	s_mov_b32 m0, s1
	s_nop 0
	global_load_lds_dwordx4 v[130:131], off
	s_mov_b32 m0, s10
	s_mov_b64 s[10:11], 0x380000
	v_lshl_add_u64 v[128:129], v[128:129], 0, s[10:11]
	s_add_i32 s0, s0, 0xe000
	s_mov_b32 s1, m0
	s_mov_b32 m0, s0
	s_nop 0
	global_load_lds_dwordx4 v[128:129], off
	s_mov_b32 m0, s1
	s_mov_b64 s[10:11], -1

.LBB0_702:
	s_add_i32 s1, s0, 0x10000
	s_and_b32 s14, s1, 0x10000
	s_and_b32 s0, s0, 0x10000
	s_add_i32 s0, s0, 16
	v_add_u32_e32 v190, s14, v161
	s_nop 0
	v_readfirstlane_b32 s14, v190
	s_waitcnt vmcnt(0)
	s_barrier
	v_add_u32_e32 v133, s0, v151
	v_add_u32_e32 v168, v133, v166
	ds_read_b128 v[178:181], v168
	ds_read_b128 v[202:205], v168 offset:4096
	ds_read_b128 v[206:209], v168 offset:8192
	ds_read_b128 v[210:213], v168 offset:12288
	v_add_u32_e32 v168, s0, v155
	v_add_u32_e32 v177, v168, v166
	ds_read_b128 v[214:217], v177 offset:32768
	ds_read_b128 v[218:221], v177 offset:36864
	v_lshl_add_u64 v[222:223], v[148:149], 0, s[2:3]
	s_mov_b32 m0, s14
	s_nop 0
	global_load_lds_dwordx4 v[222:223], off
	v_lshl_add_u64 v[222:223], v[146:147], 0, s[2:3]
	s_add_i32 s15, s14, 0x2000
	s_mov_b32 m0, s15
	s_nop 0
	global_load_lds_dwordx4 v[222:223], off
	s_waitcnt lgkmcnt(1)
	v_mfma_f32_32x32x16_bf16 v[112:127], v[214:217], v[178:181], v[112:127]
	v_lshl_add_u64 v[222:223], v[144:145], 0, s[2:3]
	s_add_i32 s15, s14, 0x4000
	s_mov_b32 m0, s15
	s_nop 0
	global_load_lds_dwordx4 v[222:223], off
	v_add_u32_e32 v177, v133, v167
	v_mfma_f32_32x32x16_bf16 v[80:95], v[214:217], v[202:205], v[80:95]
	v_lshl_add_u64 v[222:223], v[142:143], 0, s[2:3]
	s_add_i32 s15, s14, 0x6000
	s_mov_b32 m0, s15
	s_nop 0
	global_load_lds_dwordx4 v[222:223], off
	v_mfma_f32_32x32x16_bf16 v[48:63], v[214:217], v[206:209], v[48:63]
	v_lshl_add_u64 v[222:223], v[140:141], 0, s[2:3]
	s_add_i32 s15, s14, 0x8000
	s_mov_b32 m0, s15
	s_nop 0
	global_load_lds_dwordx4 v[222:223], off
	v_mfma_f32_32x32x16_bf16 v[16:31], v[214:217], v[210:213], v[16:31]
	v_lshl_add_u64 v[222:223], v[138:139], 0, s[2:3]
	s_add_i32 s15, s14, 0xa000
	s_mov_b32 m0, s15
	s_nop 0
	global_load_lds_dwordx4 v[222:223], off
	s_waitcnt lgkmcnt(0)
	v_mfma_f32_32x32x16_bf16 v[96:111], v[218:221], v[178:181], v[96:111]
	v_lshl_add_u64 v[222:223], v[136:137], 0, s[2:3]
	s_add_i32 s15, s14, 0xc000
	s_mov_b32 m0, s15
	s_nop 0
	global_load_lds_dwordx4 v[222:223], off
	v_mfma_f32_32x32x16_bf16 v[64:79], v[218:221], v[202:205], v[64:79]
	v_lshl_add_u64 v[222:223], v[134:135], 0, s[2:3]
	s_add_i32 s15, s14, 0xe000
	s_mov_b32 m0, s15
	s_nop 0
	global_load_lds_dwordx4 v[222:223], off
	s_add_u32 s2, s2, 0x80
	s_addc_u32 s3, s3, 0
	s_cmpk_eq_i32 s2, 0x780
	v_mfma_f32_32x32x16_bf16 v[32:47], v[218:221], v[206:209], v[32:47]
	v_mfma_f32_32x32x16_bf16 v[0:15], v[218:221], v[210:213], v[0:15]
	ds_read_b128 v[178:181], v177
	ds_read_b128 v[202:205], v177 offset:4096
	ds_read_b128 v[206:209], v177 offset:8192
	ds_read_b128 v[210:213], v177 offset:12288
	v_add_u32_e32 v177, v168, v167
	ds_read_b128 v[214:217], v177 offset:32768
	ds_read_b128 v[218:221], v177 offset:36864
	v_add_u32_e32 v177, v133, v170
	v_add_u32_e32 v133, v133, v171
	s_waitcnt lgkmcnt(1)
	v_mfma_f32_32x32x16_bf16 v[112:127], v[214:217], v[178:181], v[112:127]
	v_mfma_f32_32x32x16_bf16 v[80:95], v[214:217], v[202:205], v[80:95]
	v_mfma_f32_32x32x16_bf16 v[48:63], v[214:217], v[206:209], v[48:63]
	v_mfma_f32_32x32x16_bf16 v[16:31], v[214:217], v[210:213], v[16:31]
	s_waitcnt lgkmcnt(0)
	v_mfma_f32_32x32x16_bf16 v[96:111], v[218:221], v[178:181], v[96:111]
	v_mfma_f32_32x32x16_bf16 v[64:79], v[218:221], v[202:205], v[64:79]
	v_mfma_f32_32x32x16_bf16 v[32:47], v[218:221], v[206:209], v[32:47]
	v_mfma_f32_32x32x16_bf16 v[0:15], v[218:221], v[210:213], v[0:15]
	ds_read_b128 v[178:181], v177
	ds_read_b128 v[202:205], v177 offset:4096
	ds_read_b128 v[206:209], v177 offset:8192
	ds_read_b128 v[210:213], v177 offset:12288
	v_add_u32_e32 v177, v168, v170
	ds_read_b128 v[214:217], v177 offset:32768
	ds_read_b128 v[218:221], v177 offset:36864
	s_waitcnt lgkmcnt(1)
	v_mfma_f32_32x32x16_bf16 v[112:127], v[214:217], v[178:181], v[112:127]
	v_mfma_f32_32x32x16_bf16 v[80:95], v[214:217], v[202:205], v[80:95]
	v_mfma_f32_32x32x16_bf16 v[48:63], v[214:217], v[206:209], v[48:63]
	v_mfma_f32_32x32x16_bf16 v[16:31], v[214:217], v[210:213], v[16:31]
	s_waitcnt lgkmcnt(0)
	v_mfma_f32_32x32x16_bf16 v[96:111], v[218:221], v[178:181], v[96:111]
	v_mfma_f32_32x32x16_bf16 v[64:79], v[218:221], v[202:205], v[64:79]
	v_mfma_f32_32x32x16_bf16 v[32:47], v[218:221], v[206:209], v[32:47]
	v_mfma_f32_32x32x16_bf16 v[0:15], v[218:221], v[210:213], v[0:15]
	ds_read_b128 v[178:181], v133
	ds_read_b128 v[202:205], v133 offset:4096
	ds_read_b128 v[206:209], v133 offset:8192
	ds_read_b128 v[210:213], v133 offset:12288
	v_add_u32_e32 v133, v168, v171
	ds_read_b128 v[214:217], v133 offset:32768
	ds_read_b128 v[218:221], v133 offset:36864
	s_waitcnt lgkmcnt(1)
	v_mfma_f32_32x32x16_bf16 v[112:127], v[214:217], v[178:181], v[112:127]
	v_mfma_f32_32x32x16_bf16 v[80:95], v[214:217], v[202:205], v[80:95]
	v_mfma_f32_32x32x16_bf16 v[48:63], v[214:217], v[206:209], v[48:63]
	v_mfma_f32_32x32x16_bf16 v[16:31], v[214:217], v[210:213], v[16:31]
	s_waitcnt lgkmcnt(0)
	v_mfma_f32_32x32x16_bf16 v[96:111], v[218:221], v[178:181], v[96:111]
	v_mfma_f32_32x32x16_bf16 v[64:79], v[218:221], v[202:205], v[64:79]
	v_mfma_f32_32x32x16_bf16 v[32:47], v[218:221], v[206:209], v[32:47]
	v_mfma_f32_32x32x16_bf16 v[0:15], v[218:221], v[210:213], v[0:15]
	s_mov_b32 s0, s1
	s_cbranch_scc0 .LBB0_702
	s_waitcnt vmcnt(0)
	s_barrier
	v_mov_b32_e32 v133, 0x358637bd
	s_and_saveexec_b64 s[2:3], s[6:7]
	s_cbranch_execz .LBB0_705
	v_add_u32_e32 v134, s17, v150
	v_ashrrev_i32_e32 v135, 31, v134
	v_lshlrev_b64 v[134:135], 6, v[134:135]
	v_lshl_add_u64 v[146:147], s[10:11], 0, v[134:135]
	global_load_dwordx4 v[134:137], v[146:147], off
	global_load_dwordx4 v[138:141], v[146:147], off offset:16
	global_load_dwordx4 v[142:145], v[146:147], off offset:32
	s_nop 0
	global_load_dwordx4 v[146:149], v[146:147], off offset:48
	s_waitcnt vmcnt(3)
	v_mov_b32_e32 v178, v135
	v_mov_b32_e32 v179, v136
	v_mov_b32_e32 v135, v137
	v_pk_add_f32 v[134:135], v[178:179], v[134:135]
	s_waitcnt vmcnt(2)
	v_mov_b32_e32 v180, v139
	v_mov_b32_e32 v181, v140
	v_mov_b32_e32 v139, v141
	v_add_f32_e32 v133, 0, v134
	v_pk_add_f32 v[136:137], v[180:181], v[138:139]
	v_add_f32_e32 v133, v133, v135
	s_waitcnt vmcnt(1)
	v_mov_b32_e32 v182, v143
	v_mov_b32_e32 v183, v144
	v_mov_b32_e32 v143, v145
	v_add_f32_e32 v133, v133, v136
	v_pk_add_f32 v[138:139], v[182:183], v[142:143]
	v_add_f32_e32 v133, v133, v137
	s_waitcnt vmcnt(0)
	v_mov_b32_e32 v202, v147
	v_mov_b32_e32 v203, v148
	v_mov_b32_e32 v147, v149
	v_add_f32_e32 v133, v133, v138
	v_add_f32_e32 v133, v133, v139
	v_pk_add_f32 v[134:135], v[202:203], v[146:147]
	s_nop 0
	v_add_f32_e32 v133, v133, v134
	v_add_f32_e32 v133, v133, v135
	v_fmamk_f32 v133, v133, 0x3a800000, v187

.LBB0_717:
	s_add_i32 s1, s0, 0x10000
	s_and_b32 s11, s1, 0x10000
	s_and_b32 s0, s0, 0x10000
	s_add_i32 s0, s0, 16
	v_add_u32_e32 v190, s11, v210
	s_nop 0
	v_readfirstlane_b32 s11, v190
	s_waitcnt vmcnt(0)
	s_barrier
	v_add_u32_e32 v166, s0, v182
	v_add_u32_e32 v167, s0, v204
	v_add_u32_e32 v162, v166, v227
	v_add_u32_e32 v168, v167, v227
	ds_read_b128 v[150:153], v162
	ds_read_b128 v[154:157], v162 offset:4096
	ds_read_b128 v[158:161], v162 offset:8192
	ds_read_b128 v[162:165], v162 offset:12288
	ds_read_b128 v[170:173], v168 offset:32768
	ds_read_b128 v[174:177], v168 offset:36864
	v_lshl_add_u64 v[178:179], v[142:143], 0, s[2:3]
	s_mov_b32 m0, s11
	s_nop 0
	global_load_lds_dwordx4 v[178:179], off
	v_lshl_add_u64 v[178:179], v[140:141], 0, s[2:3]
	s_add_i32 s12, s11, 0x2000
	s_mov_b32 m0, s12
	s_nop 0
	global_load_lds_dwordx4 v[178:179], off
	s_waitcnt lgkmcnt(1)
	v_mfma_f32_32x32x16_bf16 v[112:127], v[170:173], v[150:153], v[112:127]
	v_lshl_add_u64 v[178:179], v[138:139], 0, s[2:3]
	s_add_i32 s12, s11, 0x4000
	s_mov_b32 m0, s12
	s_nop 0
	global_load_lds_dwordx4 v[178:179], off
	v_add_u32_e32 v168, v167, v228
	v_mfma_f32_32x32x16_bf16 v[96:111], v[170:173], v[154:157], v[96:111]
	v_lshl_add_u64 v[178:179], v[136:137], 0, s[2:3]
	s_add_i32 s12, s11, 0x6000
	s_mov_b32 m0, s12
	s_nop 0
	global_load_lds_dwordx4 v[178:179], off
	v_mfma_f32_32x32x16_bf16 v[80:95], v[170:173], v[158:161], v[80:95]
	v_lshl_add_u64 v[178:179], v[134:135], 0, s[2:3]
	s_add_i32 s12, s11, 0x8000
	s_mov_b32 m0, s12
	s_nop 0
	global_load_lds_dwordx4 v[178:179], off
	v_mfma_f32_32x32x16_bf16 v[64:79], v[170:173], v[162:165], v[64:79]
	v_lshl_add_u64 v[178:179], v[132:133], 0, s[2:3]
	s_add_i32 s12, s11, 0xa000
	s_mov_b32 m0, s12
	s_nop 0
	global_load_lds_dwordx4 v[178:179], off
	s_waitcnt lgkmcnt(0)
	v_mfma_f32_32x32x16_bf16 v[48:63], v[174:177], v[150:153], v[48:63]
	v_lshl_add_u64 v[178:179], v[130:131], 0, s[2:3]
	s_add_i32 s12, s11, 0xc000
	s_mov_b32 m0, s12
	s_nop 0
	global_load_lds_dwordx4 v[178:179], off
	v_mfma_f32_32x32x16_bf16 v[32:47], v[174:177], v[154:157], v[32:47]
	v_lshl_add_u64 v[178:179], v[128:129], 0, s[2:3]
	s_add_i32 s12, s11, 0xe000
	s_mov_b32 m0, s12
	s_nop 0
	global_load_lds_dwordx4 v[178:179], off
	s_add_u32 s2, s2, 0x80
	s_addc_u32 s3, s3, 0
	s_cmpk_lg_i32 s2, 0x780
	v_mfma_f32_32x32x16_bf16 v[16:31], v[174:177], v[158:161], v[16:31]
	v_mfma_f32_32x32x16_bf16 v[0:15], v[174:177], v[162:165], v[0:15]
	v_add_u32_e32 v162, v166, v228
	ds_read_b128 v[150:153], v162
	ds_read_b128 v[154:157], v162 offset:4096
	ds_read_b128 v[158:161], v162 offset:8192
	ds_read_b128 v[162:165], v162 offset:12288
	ds_read_b128 v[170:173], v168 offset:32768
	ds_read_b128 v[174:177], v168 offset:36864
	v_add_u32_e32 v168, v167, v229
	s_waitcnt lgkmcnt(1)
	v_mfma_f32_32x32x16_bf16 v[112:127], v[170:173], v[150:153], v[112:127]
	v_mfma_f32_32x32x16_bf16 v[96:111], v[170:173], v[154:157], v[96:111]
	v_mfma_f32_32x32x16_bf16 v[80:95], v[170:173], v[158:161], v[80:95]
	v_mfma_f32_32x32x16_bf16 v[64:79], v[170:173], v[162:165], v[64:79]
	s_waitcnt lgkmcnt(0)
	v_mfma_f32_32x32x16_bf16 v[48:63], v[174:177], v[150:153], v[48:63]
	v_mfma_f32_32x32x16_bf16 v[32:47], v[174:177], v[154:157], v[32:47]
	v_mfma_f32_32x32x16_bf16 v[16:31], v[174:177], v[158:161], v[16:31]
	v_mfma_f32_32x32x16_bf16 v[0:15], v[174:177], v[162:165], v[0:15]
	v_add_u32_e32 v162, v166, v229
	ds_read_b128 v[150:153], v162
	ds_read_b128 v[154:157], v162 offset:4096
	ds_read_b128 v[158:161], v162 offset:8192
	ds_read_b128 v[162:165], v162 offset:12288
	ds_read_b128 v[170:173], v168 offset:32768
	ds_read_b128 v[174:177], v168 offset:36864
	s_waitcnt lgkmcnt(1)
	v_mfma_f32_32x32x16_bf16 v[112:127], v[170:173], v[150:153], v[112:127]
	v_mfma_f32_32x32x16_bf16 v[96:111], v[170:173], v[154:157], v[96:111]
	v_mfma_f32_32x32x16_bf16 v[80:95], v[170:173], v[158:161], v[80:95]
	v_mfma_f32_32x32x16_bf16 v[64:79], v[170:173], v[162:165], v[64:79]
	s_waitcnt lgkmcnt(0)
	v_mfma_f32_32x32x16_bf16 v[48:63], v[174:177], v[150:153], v[48:63]
	v_mfma_f32_32x32x16_bf16 v[32:47], v[174:177], v[154:157], v[32:47]
	v_mfma_f32_32x32x16_bf16 v[16:31], v[174:177], v[158:161], v[16:31]
	v_mfma_f32_32x32x16_bf16 v[0:15], v[174:177], v[162:165], v[0:15]
	v_add_u32_e32 v162, v166, v230
	v_add_u32_e32 v166, v167, v230
	ds_read_b128 v[150:153], v162
	ds_read_b128 v[154:157], v162 offset:4096
	ds_read_b128 v[158:161], v162 offset:8192
	ds_read_b128 v[162:165], v162 offset:12288
	ds_read_b128 v[170:173], v166 offset:32768
	ds_read_b128 v[174:177], v166 offset:36864
	s_waitcnt lgkmcnt(1)
	v_mfma_f32_32x32x16_bf16 v[112:127], v[170:173], v[150:153], v[112:127]
	v_mfma_f32_32x32x16_bf16 v[96:111], v[170:173], v[154:157], v[96:111]
	v_mfma_f32_32x32x16_bf16 v[80:95], v[170:173], v[158:161], v[80:95]
	v_mfma_f32_32x32x16_bf16 v[64:79], v[170:173], v[162:165], v[64:79]
	s_waitcnt lgkmcnt(0)
	v_mfma_f32_32x32x16_bf16 v[48:63], v[174:177], v[150:153], v[48:63]
	v_mfma_f32_32x32x16_bf16 v[32:47], v[174:177], v[154:157], v[32:47]
	v_mfma_f32_32x32x16_bf16 v[16:31], v[174:177], v[158:161], v[16:31]
	v_mfma_f32_32x32x16_bf16 v[0:15], v[174:177], v[162:165], v[0:15]
	s_mov_b32 s0, s1
	s_cbranch_scc1 .LBB0_717
	s_add_i32 s21, s21, s78
	s_cmpk_gt_i32 s21, 0xff
	s_waitcnt vmcnt(0)
	s_barrier
	s_cselect_b64 s[2:3], -1, 0
	s_and_b64 vcc, exec, s[2:3]
	s_cbranch_vccnz .LBB0_720
	s_lshl_b32 s0, s21, 3
	s_and_b32 s0, s0, 56
	s_ashr_i32 s1, s21, 5
	s_add_i32 s8, s0, s1
	s_ashr_i32 s0, s8, 5
	s_ashr_i32 s1, s0, 31
	s_lshl_b32 s9, s21, 5
	v_lshl_add_u32 v130, s8, 8, v207
	s_and_b32 s9, s9, 0x300
	s_lshl_b64 s[0:1], s[0:1], 21
	v_ashrrev_i32_e32 v131, 31, v130
	v_lshlrev_b64 v[134:135], 11, v[130:131]
	s_cmp_lg_u32 16, -1
	v_lshl_add_u64 v[128:129], v[144:145], 0, s[0:1]
	v_lshl_add_u64 v[134:135], v[146:147], 0, v[134:135]
	v_readfirstlane_b32 s0, v209
	s_cselect_b32 s1, 16, 0
	s_add_i32 s0, s0, s1
	s_mov_b32 s1, m0
	s_mov_b32 m0, s0
	s_nop 0
	global_load_lds_dwordx4 v[134:135], off
	s_mov_b32 m0, s1
	v_add_u32_e32 v134, 64, v130
	v_ashrrev_i32_e32 v135, 31, v134
	v_lshlrev_b64 v[134:135], 11, v[134:135]
	v_lshl_add_u64 v[134:135], v[146:147], 0, v[134:135]
	s_add_i32 s1, s0, 0x2000
	s_mov_b32 s8, m0
	s_mov_b32 m0, s1
	s_nop 0
	global_load_lds_dwordx4 v[134:135], off
	s_mov_b32 m0, s8
	v_add_u32_e32 v134, 0x80, v130
	v_add_u32_e32 v130, 0xc0, v130
	v_ashrrev_i32_e32 v135, 31, v134
	v_ashrrev_i32_e32 v131, 31, v130
	v_add_u32_e32 v132, s9, v208
	v_lshlrev_b64 v[134:135], 11, v[134:135]
	v_lshlrev_b64 v[130:131], 11, v[130:131]
	v_lshl_add_u64 v[134:135], v[146:147], 0, v[134:135]
	s_add_i32 s1, s0, 0x4000
	s_mov_b32 s8, m0
	s_mov_b32 m0, s1
	s_nop 0
	global_load_lds_dwordx4 v[134:135], off
	s_mov_b32 m0, s8
	v_lshl_add_u64 v[130:131], v[146:147], 0, v[130:131]
	v_ashrrev_i32_e32 v133, 31, v132
	s_add_i32 s1, s0, 0x6000
	s_mov_b32 s8, m0
	s_mov_b32 m0, s1
	s_nop 0
	global_load_lds_dwordx4 v[130:131], off
	s_mov_b32 m0, s8
	v_lshlrev_b64 v[130:131], 11, v[132:133]
	v_lshl_add_u64 v[128:129], v[128:129], 0, v[130:131]
	v_lshl_add_u64 v[130:131], v[128:129], 0, s[34:35]
	s_add_i32 s1, s0, 0x8000
	s_mov_b32 s8, m0
	s_mov_b32 m0, s1
	s_nop 0
	global_load_lds_dwordx4 v[130:131], off
	s_mov_b32 m0, s8
	v_lshl_add_u64 v[130:131], v[128:129], 0, s[38:39]
	s_add_i32 s1, s0, 0xa000
	s_mov_b32 s8, m0
	s_mov_b32 m0, s1
	s_nop 0
	global_load_lds_dwordx4 v[130:131], off
	s_mov_b32 m0, s8
	v_lshl_add_u64 v[130:131], v[128:129], 0, s[36:37]
	s_add_i32 s1, s0, 0xc000
	s_mov_b32 s8, m0
	s_mov_b32 m0, s1
	s_nop 0
	global_load_lds_dwordx4 v[130:131], off
	s_mov_b32 m0, s8
	v_lshl_add_u64 v[128:129], v[128:129], 0, s[40:41]
	s_add_i32 s0, s0, 0xe000
	s_mov_b32 s1, m0
	s_mov_b32 m0, s0
	s_nop 0
	global_load_lds_dwordx4 v[128:129], off
	s_mov_b32 m0, s1
	s_mov_b64 s[8:9], -1

.LBB0_745:
	s_add_i32 s1, s0, 0x10000
	s_and_b32 s16, s1, 0x10000
	s_and_b32 s0, s0, 0x10000
	s_add_i32 s0, s0, 16
	v_add_u32_e32 v224, s16, v161
	s_nop 0
	v_readfirstlane_b32 s16, v224
	s_waitcnt vmcnt(0)
	s_barrier
	v_add_u32_e32 v133, s0, v151
	v_add_u32_e32 v168, v133, v171
	ds_read_b128 v[180:183], v168
	ds_read_b128 v[202:205], v168 offset:4096
	ds_read_b128 v[206:209], v168 offset:8192
	ds_read_b128 v[210:213], v168 offset:12288
	v_add_u32_e32 v168, s0, v155
	v_add_u32_e32 v190, v168, v171
	ds_read_b128 v[214:217], v190 offset:32768
	ds_read_b128 v[218:221], v190 offset:36864
	v_lshl_add_u64 v[222:223], v[148:149], 0, s[2:3]
	s_mov_b32 m0, s16
	s_nop 0
	global_load_lds_dwordx4 v[222:223], off
	v_lshl_add_u64 v[222:223], v[146:147], 0, s[2:3]
	s_add_i32 s17, s16, 0x2000
	s_mov_b32 m0, s17
	s_nop 0
	global_load_lds_dwordx4 v[222:223], off
	s_waitcnt lgkmcnt(1)
	v_mfma_f32_32x32x16_bf16 v[112:127], v[214:217], v[180:183], v[112:127]
	v_lshl_add_u64 v[222:223], v[144:145], 0, s[2:3]
	s_add_i32 s17, s16, 0x4000
	s_mov_b32 m0, s17
	s_nop 0
	global_load_lds_dwordx4 v[222:223], off
	v_add_u32_e32 v190, v133, v172
	v_mfma_f32_32x32x16_bf16 v[96:111], v[214:217], v[202:205], v[96:111]
	v_lshl_add_u64 v[222:223], v[142:143], 0, s[2:3]
	s_add_i32 s17, s16, 0x6000
	s_mov_b32 m0, s17
	s_nop 0
	global_load_lds_dwordx4 v[222:223], off
	v_mfma_f32_32x32x16_bf16 v[64:79], v[214:217], v[206:209], v[64:79]
	v_lshl_add_u64 v[222:223], v[140:141], 0, s[2:3]
	s_add_i32 s17, s16, 0x8000
	s_mov_b32 m0, s17
	s_nop 0
	global_load_lds_dwordx4 v[222:223], off
	v_mfma_f32_32x32x16_bf16 v[32:47], v[214:217], v[210:213], v[32:47]
	v_lshl_add_u64 v[222:223], v[138:139], 0, s[2:3]
	s_add_i32 s17, s16, 0xa000
	s_mov_b32 m0, s17
	s_nop 0
	global_load_lds_dwordx4 v[222:223], off
	s_waitcnt lgkmcnt(0)
	v_mfma_f32_32x32x16_bf16 v[80:95], v[218:221], v[180:183], v[80:95]
	v_lshl_add_u64 v[222:223], v[136:137], 0, s[2:3]
	s_add_i32 s17, s16, 0xc000
	s_mov_b32 m0, s17
	s_nop 0
	global_load_lds_dwordx4 v[222:223], off
	v_mfma_f32_32x32x16_bf16 v[48:63], v[218:221], v[202:205], v[48:63]
	v_lshl_add_u64 v[222:223], v[134:135], 0, s[2:3]
	s_add_i32 s17, s16, 0xe000
	s_mov_b32 m0, s17
	s_nop 0
	global_load_lds_dwordx4 v[222:223], off
	s_add_u32 s2, s2, 0x80
	s_addc_u32 s3, s3, 0
	s_cmpk_eq_i32 s2, 0x780
	v_mfma_f32_32x32x16_bf16 v[16:31], v[218:221], v[206:209], v[16:31]
	v_mfma_f32_32x32x16_bf16 v[0:15], v[218:221], v[210:213], v[0:15]
	ds_read_b128 v[180:183], v190
	ds_read_b128 v[202:205], v190 offset:4096
	ds_read_b128 v[206:209], v190 offset:8192
	ds_read_b128 v[210:213], v190 offset:12288
	v_add_u32_e32 v190, v168, v172
	ds_read_b128 v[214:217], v190 offset:32768
	ds_read_b128 v[218:221], v190 offset:36864
	v_add_u32_e32 v190, v133, v173
	v_add_u32_e32 v133, v133, v174
	s_waitcnt lgkmcnt(1)
	v_mfma_f32_32x32x16_bf16 v[112:127], v[214:217], v[180:183], v[112:127]
	v_mfma_f32_32x32x16_bf16 v[96:111], v[214:217], v[202:205], v[96:111]
	v_mfma_f32_32x32x16_bf16 v[64:79], v[214:217], v[206:209], v[64:79]
	v_mfma_f32_32x32x16_bf16 v[32:47], v[214:217], v[210:213], v[32:47]
	s_waitcnt lgkmcnt(0)
	v_mfma_f32_32x32x16_bf16 v[80:95], v[218:221], v[180:183], v[80:95]
	v_mfma_f32_32x32x16_bf16 v[48:63], v[218:221], v[202:205], v[48:63]
	v_mfma_f32_32x32x16_bf16 v[16:31], v[218:221], v[206:209], v[16:31]
	v_mfma_f32_32x32x16_bf16 v[0:15], v[218:221], v[210:213], v[0:15]
	ds_read_b128 v[180:183], v190
	ds_read_b128 v[202:205], v190 offset:4096
	ds_read_b128 v[206:209], v190 offset:8192
	ds_read_b128 v[210:213], v190 offset:12288
	v_add_u32_e32 v190, v168, v173
	ds_read_b128 v[214:217], v190 offset:32768
	ds_read_b128 v[218:221], v190 offset:36864
	s_waitcnt lgkmcnt(1)
	v_mfma_f32_32x32x16_bf16 v[112:127], v[214:217], v[180:183], v[112:127]
	v_mfma_f32_32x32x16_bf16 v[96:111], v[214:217], v[202:205], v[96:111]
	v_mfma_f32_32x32x16_bf16 v[64:79], v[214:217], v[206:209], v[64:79]
	v_mfma_f32_32x32x16_bf16 v[32:47], v[214:217], v[210:213], v[32:47]
	s_waitcnt lgkmcnt(0)
	v_mfma_f32_32x32x16_bf16 v[80:95], v[218:221], v[180:183], v[80:95]
	v_mfma_f32_32x32x16_bf16 v[48:63], v[218:221], v[202:205], v[48:63]
	v_mfma_f32_32x32x16_bf16 v[16:31], v[218:221], v[206:209], v[16:31]
	v_mfma_f32_32x32x16_bf16 v[0:15], v[218:221], v[210:213], v[0:15]
	ds_read_b128 v[180:183], v133
	ds_read_b128 v[202:205], v133 offset:4096
	ds_read_b128 v[206:209], v133 offset:8192
	ds_read_b128 v[210:213], v133 offset:12288
	v_add_u32_e32 v133, v168, v174
	ds_read_b128 v[214:217], v133 offset:32768
	ds_read_b128 v[218:221], v133 offset:36864
	s_waitcnt lgkmcnt(1)
	v_mfma_f32_32x32x16_bf16 v[112:127], v[214:217], v[180:183], v[112:127]
	v_mfma_f32_32x32x16_bf16 v[96:111], v[214:217], v[202:205], v[96:111]
	v_mfma_f32_32x32x16_bf16 v[64:79], v[214:217], v[206:209], v[64:79]
	v_mfma_f32_32x32x16_bf16 v[32:47], v[214:217], v[210:213], v[32:47]
	s_waitcnt lgkmcnt(0)
	v_mfma_f32_32x32x16_bf16 v[80:95], v[218:221], v[180:183], v[80:95]
	v_mfma_f32_32x32x16_bf16 v[48:63], v[218:221], v[202:205], v[48:63]
	v_mfma_f32_32x32x16_bf16 v[16:31], v[218:221], v[206:209], v[16:31]
	v_mfma_f32_32x32x16_bf16 v[0:15], v[218:221], v[210:213], v[0:15]
	s_mov_b32 s0, s1
	s_cbranch_scc0 .LBB0_745
	s_waitcnt vmcnt(0)
	s_barrier
	v_mov_b32_e32 v133, 0x358637bd
	s_and_saveexec_b64 s[2:3], s[6:7]
	s_cbranch_execz .LBB0_748
	v_add_u32_e32 v134, s19, v150
	v_ashrrev_i32_e32 v135, 31, v134
	v_lshlrev_b64 v[134:135], 6, v[134:135]
	v_lshl_add_u64 v[146:147], s[12:13], 0, v[134:135]
	global_load_dwordx4 v[134:137], v[146:147], off
	global_load_dwordx4 v[138:141], v[146:147], off offset:16
	global_load_dwordx4 v[142:145], v[146:147], off offset:32
	s_nop 0
	global_load_dwordx4 v[146:149], v[146:147], off offset:48
	s_waitcnt vmcnt(3)
	v_mov_b32_e32 v180, v135
	v_mov_b32_e32 v181, v136
	v_mov_b32_e32 v135, v137
	v_pk_add_f32 v[134:135], v[180:181], v[134:135]
	s_waitcnt vmcnt(2)
	v_mov_b32_e32 v182, v139
	v_mov_b32_e32 v183, v140
	v_mov_b32_e32 v139, v141
	v_add_f32_e32 v133, 0, v134
	v_pk_add_f32 v[136:137], v[182:183], v[138:139]
	v_add_f32_e32 v133, v133, v135
	s_waitcnt vmcnt(1)
	v_mov_b32_e32 v202, v143
	v_mov_b32_e32 v203, v144
	v_mov_b32_e32 v143, v145
	v_add_f32_e32 v133, v133, v136
	v_pk_add_f32 v[138:139], v[202:203], v[142:143]
	v_add_f32_e32 v133, v133, v137
	s_waitcnt vmcnt(0)
	v_mov_b32_e32 v204, v147
	v_mov_b32_e32 v205, v148
	v_mov_b32_e32 v147, v149
	v_add_f32_e32 v133, v133, v138
	v_add_f32_e32 v133, v133, v139
	v_pk_add_f32 v[134:135], v[204:205], v[146:147]
	s_nop 0
	v_add_f32_e32 v133, v133, v134
	v_add_f32_e32 v133, v133, v135
	v_fmamk_f32 v133, v133, 0x3a800000, v187

.LBB0_778:
	s_add_i32 s1, s0, 0x10000
	s_and_b32 s11, s1, 0x10000
	s_and_b32 s0, s0, 0x10000
	s_add_i32 s0, s0, 16
	v_add_u32_e32 v190, s11, v210
	s_nop 0
	v_readfirstlane_b32 s11, v190
	s_waitcnt vmcnt(0)
	s_barrier
	v_add_u32_e32 v166, s0, v182
	v_add_u32_e32 v167, s0, v204
	v_add_u32_e32 v162, v166, v227
	v_add_u32_e32 v168, v167, v227
	ds_read_b128 v[150:153], v162
	ds_read_b128 v[154:157], v162 offset:4096
	ds_read_b128 v[158:161], v162 offset:8192
	ds_read_b128 v[162:165], v162 offset:12288
	ds_read_b128 v[170:173], v168 offset:32768
	ds_read_b128 v[174:177], v168 offset:36864
	v_lshl_add_u64 v[178:179], v[142:143], 0, s[2:3]
	s_mov_b32 m0, s11
	s_nop 0
	global_load_lds_dwordx4 v[178:179], off
	v_lshl_add_u64 v[178:179], v[140:141], 0, s[2:3]
	s_add_i32 s12, s11, 0x2000
	s_mov_b32 m0, s12
	s_nop 0
	global_load_lds_dwordx4 v[178:179], off
	s_waitcnt lgkmcnt(1)
	v_mfma_f32_32x32x16_bf16 v[112:127], v[170:173], v[150:153], v[112:127]
	v_lshl_add_u64 v[178:179], v[138:139], 0, s[2:3]
	s_add_i32 s12, s11, 0x4000
	s_mov_b32 m0, s12
	s_nop 0
	global_load_lds_dwordx4 v[178:179], off
	v_add_u32_e32 v168, v167, v228
	v_mfma_f32_32x32x16_bf16 v[96:111], v[170:173], v[154:157], v[96:111]
	v_lshl_add_u64 v[178:179], v[136:137], 0, s[2:3]
	s_add_i32 s12, s11, 0x6000
	s_mov_b32 m0, s12
	s_nop 0
	global_load_lds_dwordx4 v[178:179], off
	v_mfma_f32_32x32x16_bf16 v[80:95], v[170:173], v[158:161], v[80:95]
	v_lshl_add_u64 v[178:179], v[134:135], 0, s[2:3]
	s_add_i32 s12, s11, 0x8000
	s_mov_b32 m0, s12
	s_nop 0
	global_load_lds_dwordx4 v[178:179], off
	v_mfma_f32_32x32x16_bf16 v[64:79], v[170:173], v[162:165], v[64:79]
	v_lshl_add_u64 v[178:179], v[132:133], 0, s[2:3]
	s_add_i32 s12, s11, 0xa000
	s_mov_b32 m0, s12
	s_nop 0
	global_load_lds_dwordx4 v[178:179], off
	s_waitcnt lgkmcnt(0)
	v_mfma_f32_32x32x16_bf16 v[48:63], v[174:177], v[150:153], v[48:63]
	v_lshl_add_u64 v[178:179], v[130:131], 0, s[2:3]
	s_add_i32 s12, s11, 0xc000
	s_mov_b32 m0, s12
	s_nop 0
	global_load_lds_dwordx4 v[178:179], off
	v_mfma_f32_32x32x16_bf16 v[32:47], v[174:177], v[154:157], v[32:47]
	v_lshl_add_u64 v[178:179], v[128:129], 0, s[2:3]
	s_add_i32 s12, s11, 0xe000
	s_mov_b32 m0, s12
	s_nop 0
	global_load_lds_dwordx4 v[178:179], off
	s_add_u32 s2, s2, 0x80
	s_addc_u32 s3, s3, 0
	s_cmpk_lg_i32 s2, 0x780
	v_mfma_f32_32x32x16_bf16 v[16:31], v[174:177], v[158:161], v[16:31]
	v_mfma_f32_32x32x16_bf16 v[0:15], v[174:177], v[162:165], v[0:15]
	v_add_u32_e32 v162, v166, v228
	ds_read_b128 v[150:153], v162
	ds_read_b128 v[154:157], v162 offset:4096
	ds_read_b128 v[158:161], v162 offset:8192
	ds_read_b128 v[162:165], v162 offset:12288
	ds_read_b128 v[170:173], v168 offset:32768
	ds_read_b128 v[174:177], v168 offset:36864
	v_add_u32_e32 v168, v167, v229
	s_waitcnt lgkmcnt(1)
	v_mfma_f32_32x32x16_bf16 v[112:127], v[170:173], v[150:153], v[112:127]
	v_mfma_f32_32x32x16_bf16 v[96:111], v[170:173], v[154:157], v[96:111]
	v_mfma_f32_32x32x16_bf16 v[80:95], v[170:173], v[158:161], v[80:95]
	v_mfma_f32_32x32x16_bf16 v[64:79], v[170:173], v[162:165], v[64:79]
	s_waitcnt lgkmcnt(0)
	v_mfma_f32_32x32x16_bf16 v[48:63], v[174:177], v[150:153], v[48:63]
	v_mfma_f32_32x32x16_bf16 v[32:47], v[174:177], v[154:157], v[32:47]
	v_mfma_f32_32x32x16_bf16 v[16:31], v[174:177], v[158:161], v[16:31]
	v_mfma_f32_32x32x16_bf16 v[0:15], v[174:177], v[162:165], v[0:15]
	v_add_u32_e32 v162, v166, v229
	ds_read_b128 v[150:153], v162
	ds_read_b128 v[154:157], v162 offset:4096
	ds_read_b128 v[158:161], v162 offset:8192
	ds_read_b128 v[162:165], v162 offset:12288
	ds_read_b128 v[170:173], v168 offset:32768
	ds_read_b128 v[174:177], v168 offset:36864
	s_waitcnt lgkmcnt(1)
	v_mfma_f32_32x32x16_bf16 v[112:127], v[170:173], v[150:153], v[112:127]
	v_mfma_f32_32x32x16_bf16 v[96:111], v[170:173], v[154:157], v[96:111]
	v_mfma_f32_32x32x16_bf16 v[80:95], v[170:173], v[158:161], v[80:95]
	v_mfma_f32_32x32x16_bf16 v[64:79], v[170:173], v[162:165], v[64:79]
	s_waitcnt lgkmcnt(0)
	v_mfma_f32_32x32x16_bf16 v[48:63], v[174:177], v[150:153], v[48:63]
	v_mfma_f32_32x32x16_bf16 v[32:47], v[174:177], v[154:157], v[32:47]
	v_mfma_f32_32x32x16_bf16 v[16:31], v[174:177], v[158:161], v[16:31]
	v_mfma_f32_32x32x16_bf16 v[0:15], v[174:177], v[162:165], v[0:15]
	v_add_u32_e32 v162, v166, v230
	v_add_u32_e32 v166, v167, v230
	ds_read_b128 v[150:153], v162
	ds_read_b128 v[154:157], v162 offset:4096
	ds_read_b128 v[158:161], v162 offset:8192
	ds_read_b128 v[162:165], v162 offset:12288
	ds_read_b128 v[170:173], v166 offset:32768
	ds_read_b128 v[174:177], v166 offset:36864
	s_waitcnt lgkmcnt(1)
	v_mfma_f32_32x32x16_bf16 v[112:127], v[170:173], v[150:153], v[112:127]
	v_mfma_f32_32x32x16_bf16 v[96:111], v[170:173], v[154:157], v[96:111]
	v_mfma_f32_32x32x16_bf16 v[80:95], v[170:173], v[158:161], v[80:95]
	v_mfma_f32_32x32x16_bf16 v[64:79], v[170:173], v[162:165], v[64:79]
	s_waitcnt lgkmcnt(0)
	v_mfma_f32_32x32x16_bf16 v[48:63], v[174:177], v[150:153], v[48:63]
	v_mfma_f32_32x32x16_bf16 v[32:47], v[174:177], v[154:157], v[32:47]
	v_mfma_f32_32x32x16_bf16 v[16:31], v[174:177], v[158:161], v[16:31]
	v_mfma_f32_32x32x16_bf16 v[0:15], v[174:177], v[162:165], v[0:15]
	s_mov_b32 s0, s1
	s_cbranch_scc1 .LBB0_778
	s_add_i32 s21, s21, s78
	s_cmpk_gt_i32 s21, 0xff
	s_waitcnt vmcnt(0)
	s_barrier
	s_cselect_b64 s[2:3], -1, 0
	s_and_b64 vcc, exec, s[2:3]
	s_cbranch_vccnz .LBB0_781
	s_lshl_b32 s0, s21, 3
	s_lshr_b32 s1, s21, 5
	s_and_b32 s0, s0, 56
	s_add_i32 s0, s0, s1
	s_lshl_b32 s8, s21, 5
	v_lshl_add_u32 v130, s0, 8, v207
	s_and_b32 s8, s8, 0x300
	v_ashrrev_i32_e32 v131, 31, v130
	v_lshlrev_b64 v[132:133], 11, v[130:131]
	s_cmp_lg_u32 16, -1
	v_lshl_add_u64 v[132:133], v[146:147], 0, v[132:133]
	v_readfirstlane_b32 s0, v209
	s_cselect_b32 s1, 16, 0
	s_add_i32 s0, s0, s1
	s_mov_b32 s1, m0
	s_mov_b32 m0, s0
	s_nop 0
	global_load_lds_dwordx4 v[132:133], off
	s_mov_b32 m0, s1
	v_add_u32_e32 v132, 64, v130
	v_ashrrev_i32_e32 v133, 31, v132
	v_lshlrev_b64 v[132:133], 11, v[132:133]
	v_lshl_add_u64 v[132:133], v[146:147], 0, v[132:133]
	v_add_u32_e32 v128, s8, v208
	s_add_i32 s1, s0, 0x2000
	s_mov_b32 s8, m0
	s_mov_b32 m0, s1
	s_nop 0
	global_load_lds_dwordx4 v[132:133], off
	s_mov_b32 m0, s8
	v_add_u32_e32 v132, 0x80, v130
	v_ashrrev_i32_e32 v133, 31, v132
	v_add_u32_e32 v130, 0xc0, v130
	v_lshlrev_b64 v[132:133], 11, v[132:133]
	v_ashrrev_i32_e32 v131, 31, v130
	v_ashrrev_i32_e32 v129, 31, v128
	v_lshl_add_u64 v[132:133], v[146:147], 0, v[132:133]
	s_add_i32 s1, s0, 0x4000
	s_mov_b32 s8, m0
	s_mov_b32 m0, s1
	s_nop 0
	global_load_lds_dwordx4 v[132:133], off
	s_mov_b32 m0, s8
	v_lshlrev_b64 v[130:131], 11, v[130:131]
	v_lshlrev_b64 v[128:129], 11, v[128:129]
	v_lshl_add_u64 v[130:131], v[146:147], 0, v[130:131]
	s_add_i32 s1, s0, 0x6000
	s_mov_b32 s8, m0
	s_mov_b32 m0, s1
	s_nop 0
	global_load_lds_dwordx4 v[130:131], off
	s_mov_b32 m0, s8
	v_lshl_add_u64 v[128:129], v[144:145], 0, v[128:129]
	v_lshl_add_u64 v[130:131], v[128:129], 0, s[34:35]
	s_add_i32 s1, s0, 0x8000
	s_mov_b32 s8, m0
	s_mov_b32 m0, s1
	s_nop 0
	global_load_lds_dwordx4 v[130:131], off
	s_mov_b32 m0, s8
	v_lshl_add_u64 v[130:131], v[128:129], 0, s[38:39]
	s_add_i32 s1, s0, 0xa000
	s_mov_b32 s8, m0
	s_mov_b32 m0, s1
	s_nop 0
	global_load_lds_dwordx4 v[130:131], off
	s_mov_b32 m0, s8
	v_lshl_add_u64 v[130:131], v[128:129], 0, s[36:37]
	s_add_i32 s1, s0, 0xc000
	s_mov_b32 s8, m0
	s_mov_b32 m0, s1
	s_nop 0
	global_load_lds_dwordx4 v[130:131], off
	s_mov_b32 m0, s8
	v_lshl_add_u64 v[128:129], v[128:129], 0, s[40:41]
	s_add_i32 s0, s0, 0xe000
	s_mov_b32 s1, m0
	s_mov_b32 m0, s0
	s_nop 0
	global_load_lds_dwordx4 v[128:129], off
	s_mov_b32 m0, s1
	s_mov_b64 s[8:9], -1

.LBB0_1265:
	s_add_i32 s1, s0, 0x10000
	s_and_b32 s12, s1, 0x10000
	s_and_b32 s0, s0, 0x10000
	s_add_i32 s0, s0, 16
	v_add_u32_e32 v190, s12, v160
	s_nop 0
	v_readfirstlane_b32 s12, v190
	s_waitcnt vmcnt(0)
	s_barrier
	v_add_u32_e32 v177, s0, v150
	v_add_u32_e32 v182, v177, v166
	ds_read_b128 v[178:181], v182
	ds_read_b128 v[202:205], v182 offset:4096
	ds_read_b128 v[206:209], v182 offset:8192
	ds_read_b128 v[210:213], v182 offset:12288
	v_add_u32_e32 v182, s0, v154
	v_add_u32_e32 v183, v182, v166
	ds_read_b128 v[214:217], v183 offset:32768
	ds_read_b128 v[218:221], v183 offset:36864
	v_lshl_add_u64 v[222:223], v[148:149], 0, s[2:3]
	s_mov_b32 m0, s12
	s_nop 0
	global_load_lds_dwordx4 v[222:223], off
	v_lshl_add_u64 v[222:223], v[146:147], 0, s[2:3]
	s_add_i32 s13, s12, 0x2000
	s_mov_b32 m0, s13
	s_nop 0
	global_load_lds_dwordx4 v[222:223], off
	s_waitcnt lgkmcnt(1)
	v_mfma_f32_32x32x16_bf16 v[112:127], v[214:217], v[178:181], v[112:127]
	v_lshl_add_u64 v[222:223], v[144:145], 0, s[2:3]
	s_add_i32 s13, s12, 0x4000
	s_mov_b32 m0, s13
	s_nop 0
	global_load_lds_dwordx4 v[222:223], off
	v_add_u32_e32 v183, v177, v167
	v_mfma_f32_32x32x16_bf16 v[80:95], v[214:217], v[202:205], v[80:95]
	v_lshl_add_u64 v[222:223], v[142:143], 0, s[2:3]
	s_add_i32 s13, s12, 0x6000
	s_mov_b32 m0, s13
	s_nop 0
	global_load_lds_dwordx4 v[222:223], off
	v_mfma_f32_32x32x16_bf16 v[48:63], v[214:217], v[206:209], v[48:63]
	v_lshl_add_u64 v[222:223], v[140:141], 0, s[2:3]
	s_add_i32 s13, s12, 0x8000
	s_mov_b32 m0, s13
	s_nop 0
	global_load_lds_dwordx4 v[222:223], off
	v_mfma_f32_32x32x16_bf16 v[16:31], v[214:217], v[210:213], v[16:31]
	v_lshl_add_u64 v[222:223], v[138:139], 0, s[2:3]
	s_add_i32 s13, s12, 0xa000
	s_mov_b32 m0, s13
	s_nop 0
	global_load_lds_dwordx4 v[222:223], off
	s_waitcnt lgkmcnt(0)
	v_mfma_f32_32x32x16_bf16 v[96:111], v[218:221], v[178:181], v[96:111]
	v_lshl_add_u64 v[222:223], v[136:137], 0, s[2:3]
	s_add_i32 s13, s12, 0xc000
	s_mov_b32 m0, s13
	s_nop 0
	global_load_lds_dwordx4 v[222:223], off
	v_mfma_f32_32x32x16_bf16 v[64:79], v[218:221], v[202:205], v[64:79]
	v_lshl_add_u64 v[222:223], v[134:135], 0, s[2:3]
	s_add_i32 s13, s12, 0xe000
	s_mov_b32 m0, s13
	s_nop 0
	global_load_lds_dwordx4 v[222:223], off
	s_add_u32 s2, s2, 0x80
	s_addc_u32 s3, s3, 0
	s_cmpk_eq_i32 s2, 0x780
	v_mfma_f32_32x32x16_bf16 v[32:47], v[218:221], v[206:209], v[32:47]
	v_mfma_f32_32x32x16_bf16 v[0:15], v[218:221], v[210:213], v[0:15]
	ds_read_b128 v[178:181], v183
	ds_read_b128 v[202:205], v183 offset:4096
	ds_read_b128 v[206:209], v183 offset:8192
	ds_read_b128 v[210:213], v183 offset:12288
	v_add_u32_e32 v183, v182, v167
	ds_read_b128 v[214:217], v183 offset:32768
	ds_read_b128 v[218:221], v183 offset:36864
	v_add_u32_e32 v183, v177, v170
	v_add_u32_e32 v177, v177, v171
	s_waitcnt lgkmcnt(1)
	v_mfma_f32_32x32x16_bf16 v[112:127], v[214:217], v[178:181], v[112:127]
	v_mfma_f32_32x32x16_bf16 v[80:95], v[214:217], v[202:205], v[80:95]
	v_mfma_f32_32x32x16_bf16 v[48:63], v[214:217], v[206:209], v[48:63]
	v_mfma_f32_32x32x16_bf16 v[16:31], v[214:217], v[210:213], v[16:31]
	s_waitcnt lgkmcnt(0)
	v_mfma_f32_32x32x16_bf16 v[96:111], v[218:221], v[178:181], v[96:111]
	v_mfma_f32_32x32x16_bf16 v[64:79], v[218:221], v[202:205], v[64:79]
	v_mfma_f32_32x32x16_bf16 v[32:47], v[218:221], v[206:209], v[32:47]
	v_mfma_f32_32x32x16_bf16 v[0:15], v[218:221], v[210:213], v[0:15]
	ds_read_b128 v[178:181], v183
	ds_read_b128 v[202:205], v183 offset:4096
	ds_read_b128 v[206:209], v183 offset:8192
	ds_read_b128 v[210:213], v183 offset:12288
	v_add_u32_e32 v183, v182, v170
	ds_read_b128 v[214:217], v183 offset:32768
	ds_read_b128 v[218:221], v183 offset:36864
	s_waitcnt lgkmcnt(1)
	v_mfma_f32_32x32x16_bf16 v[112:127], v[214:217], v[178:181], v[112:127]
	v_mfma_f32_32x32x16_bf16 v[80:95], v[214:217], v[202:205], v[80:95]
	v_mfma_f32_32x32x16_bf16 v[48:63], v[214:217], v[206:209], v[48:63]
	v_mfma_f32_32x32x16_bf16 v[16:31], v[214:217], v[210:213], v[16:31]
	s_waitcnt lgkmcnt(0)
	v_mfma_f32_32x32x16_bf16 v[96:111], v[218:221], v[178:181], v[96:111]
	v_mfma_f32_32x32x16_bf16 v[64:79], v[218:221], v[202:205], v[64:79]
	v_mfma_f32_32x32x16_bf16 v[32:47], v[218:221], v[206:209], v[32:47]
	v_mfma_f32_32x32x16_bf16 v[0:15], v[218:221], v[210:213], v[0:15]
	ds_read_b128 v[178:181], v177
	ds_read_b128 v[202:205], v177 offset:4096
	ds_read_b128 v[206:209], v177 offset:8192
	ds_read_b128 v[210:213], v177 offset:12288
	v_add_u32_e32 v177, v182, v171
	ds_read_b128 v[214:217], v177 offset:32768
	ds_read_b128 v[218:221], v177 offset:36864
	s_waitcnt lgkmcnt(1)
	v_mfma_f32_32x32x16_bf16 v[112:127], v[214:217], v[178:181], v[112:127]
	v_mfma_f32_32x32x16_bf16 v[80:95], v[214:217], v[202:205], v[80:95]
	v_mfma_f32_32x32x16_bf16 v[48:63], v[214:217], v[206:209], v[48:63]
	v_mfma_f32_32x32x16_bf16 v[16:31], v[214:217], v[210:213], v[16:31]
	s_waitcnt lgkmcnt(0)
	v_mfma_f32_32x32x16_bf16 v[96:111], v[218:221], v[178:181], v[96:111]
	v_mfma_f32_32x32x16_bf16 v[64:79], v[218:221], v[202:205], v[64:79]
	v_mfma_f32_32x32x16_bf16 v[32:47], v[218:221], v[206:209], v[32:47]
	v_mfma_f32_32x32x16_bf16 v[0:15], v[218:221], v[210:213], v[0:15]
	s_mov_b32 s0, s1
	s_cbranch_scc0 .LBB0_1265
	s_waitcnt vmcnt(0)
	s_barrier
	v_mov_b32_e32 v134, 0x358637bd
	s_and_saveexec_b64 s[2:3], s[6:7]
	s_cbranch_execz .LBB0_1268
	v_add_u32_e32 v134, s10, v129
	v_ashrrev_i32_e32 v135, 31, v134
	v_lshlrev_b64 v[134:135], 6, v[134:135]
	v_lshl_add_u64 v[146:147], s[72:73], 0, v[134:135]
	global_load_dwordx4 v[134:137], v[146:147], off
	global_load_dwordx4 v[138:141], v[146:147], off offset:16
	global_load_dwordx4 v[142:145], v[146:147], off offset:32
	s_nop 0
	global_load_dwordx4 v[146:149], v[146:147], off offset:48
	s_waitcnt vmcnt(3)
	v_mov_b32_e32 v178, v135
	v_mov_b32_e32 v179, v136
	v_mov_b32_e32 v135, v137
	v_pk_add_f32 v[134:135], v[178:179], v[134:135]
	s_waitcnt vmcnt(2)
	v_mov_b32_e32 v180, v139
	v_mov_b32_e32 v181, v140
	v_mov_b32_e32 v139, v141
	v_add_f32_e32 v134, 0, v134
	v_pk_add_f32 v[136:137], v[180:181], v[138:139]
	v_add_f32_e32 v134, v134, v135
	s_waitcnt vmcnt(1)
	v_mov_b32_e32 v182, v143
	v_mov_b32_e32 v183, v144
	v_mov_b32_e32 v143, v145
	v_add_f32_e32 v134, v134, v136
	v_pk_add_f32 v[138:139], v[182:183], v[142:143]
	v_add_f32_e32 v134, v134, v137
	s_waitcnt vmcnt(0)
	v_mov_b32_e32 v202, v147
	v_mov_b32_e32 v203, v148
	v_mov_b32_e32 v147, v149
	v_add_f32_e32 v134, v134, v138
	v_add_f32_e32 v136, v134, v139
	v_pk_add_f32 v[134:135], v[202:203], v[146:147]
	s_nop 0
	v_add_f32_e32 v134, v136, v134
	v_add_f32_e32 v134, v134, v135
	v_fmamk_f32 v134, v134, 0x3a800000, v187
